# v35 + loop-tail scalar updates and compare moved above the last barrier of each GEMM loop (out of the next load segment's head)
# baseline (speedup 1.0000x reference)
.Lpeelmid_81:
	s_add_i32 s3, 0, 0x18000
	v_add_u32_e32 v164, s3, v145
	s_add_i32 s4, 0, 0x1c000
	ds_read_b128 v[140:143], v164
	ds_read_b128 v[148:151], v164 offset:1024
	ds_read_b128 v[172:175], v164 offset:2048
	ds_read_b128 v[190:193], v164 offset:3072
	v_add_u32_e32 v164, s4, v145
	ds_read_b128 v[194:197], v164
	ds_read_b128 v[198:201], v164 offset:1024
	ds_read_b128 v[202:205], v164 offset:2048
	ds_read_b128 v[206:209], v164 offset:3072
	s_add_u32 s0, s26, 0x208000
	s_addc_u32 s1, s27, 0
	s_mov_b32 m0, s34
	ds_read_b128 v[210:213], v147 offset:32768
	ds_read_b128 v[214:217], v147 offset:33792
	ds_read_b128 v[218:221], v147 offset:34816
	ds_read_b128 v[222:225], v147 offset:35840
	ds_read_b128 v[226:229], v147 offset:36864
	ds_read_b128 v[230:233], v147 offset:37888
	ds_read_b128 v[234:237], v147 offset:38912
	ds_read_b128 v[238:241], v147 offset:39936
	global_load_lds_dwordx4 v134, s[0:1]
	v_lshl_add_u64 v[242:243], s[0:1], 0, v[132:133]
	s_mov_b32 m0, s35
	s_nop 0
	global_load_lds_dwordx4 v132, s[0:1]
	s_waitcnt vmcnt(8) lgkmcnt(0)
	s_barrier
	v_mfma_f32_16x16x32_bf16 v[126:129], v[140:143], v[210:213], v[126:129]
	v_mfma_f32_16x16x32_bf16 v[122:125], v[172:175], v[210:213], v[122:125]
	v_mfma_f32_16x16x32_bf16 v[110:113], v[140:143], v[218:221], v[110:113]
	v_mfma_f32_16x16x32_bf16 v[106:109], v[172:175], v[218:221], v[106:109]
	v_mfma_f32_16x16x32_bf16 v[94:97], v[140:143], v[226:229], v[94:97]
	v_mfma_f32_16x16x32_bf16 v[90:93], v[172:175], v[226:229], v[90:93]
	v_mfma_f32_16x16x32_bf16 v[78:81], v[140:143], v[234:237], v[78:81]
	v_mfma_f32_16x16x32_bf16 v[74:77], v[172:175], v[234:237], v[74:77]
	v_mfma_f32_16x16x32_bf16 v[126:129], v[148:151], v[214:217], v[126:129]
	v_mfma_f32_16x16x32_bf16 v[122:125], v[190:193], v[214:217], v[122:125]
	v_mfma_f32_16x16x32_bf16 v[110:113], v[148:151], v[222:225], v[110:113]
	v_mfma_f32_16x16x32_bf16 v[106:109], v[190:193], v[222:225], v[106:109]
	v_mfma_f32_16x16x32_bf16 v[94:97], v[148:151], v[230:233], v[94:97]
	v_mfma_f32_16x16x32_bf16 v[90:93], v[190:193], v[230:233], v[90:93]
	v_mfma_f32_16x16x32_bf16 v[78:81], v[148:151], v[238:241], v[78:81]
	v_mfma_f32_16x16x32_bf16 v[74:77], v[190:193], v[238:241], v[74:77]
	v_mfma_f32_16x16x32_bf16 v[118:121], v[194:197], v[210:213], v[118:121]
	v_mfma_f32_16x16x32_bf16 v[114:117], v[202:205], v[210:213], v[114:117]
	v_mfma_f32_16x16x32_bf16 v[102:105], v[194:197], v[218:221], v[102:105]
	v_mfma_f32_16x16x32_bf16 v[98:101], v[202:205], v[218:221], v[98:101]
	v_mfma_f32_16x16x32_bf16 v[86:89], v[194:197], v[226:229], v[86:89]
	v_mfma_f32_16x16x32_bf16 v[82:85], v[202:205], v[226:229], v[82:85]
	v_mfma_f32_16x16x32_bf16 v[70:73], v[194:197], v[234:237], v[70:73]
	v_mfma_f32_16x16x32_bf16 v[66:69], v[202:205], v[234:237], v[66:69]
	v_mfma_f32_16x16x32_bf16 v[118:121], v[198:201], v[214:217], v[118:121]
	v_mfma_f32_16x16x32_bf16 v[114:117], v[206:209], v[214:217], v[114:117]
	v_mfma_f32_16x16x32_bf16 v[102:105], v[198:201], v[222:225], v[102:105]
	v_mfma_f32_16x16x32_bf16 v[98:101], v[206:209], v[222:225], v[98:101]
	v_mfma_f32_16x16x32_bf16 v[86:89], v[198:201], v[230:233], v[86:89]
	v_mfma_f32_16x16x32_bf16 v[82:85], v[206:209], v[230:233], v[82:85]
	v_mfma_f32_16x16x32_bf16 v[70:73], v[198:201], v[238:241], v[70:73]
	v_mfma_f32_16x16x32_bf16 v[66:69], v[206:209], v[238:241], v[66:69]
	s_barrier
	s_add_i32 s0, s3, s11
	v_lshl_add_u64 v[162:163], v[162:163], 0, s[70:71]
	s_mov_b32 m0, s0
	ds_read_b128 v[210:213], v147 offset:49152
	ds_read_b128 v[214:217], v147 offset:50176
	ds_read_b128 v[218:221], v147 offset:51200
	ds_read_b128 v[222:225], v147 offset:52224
	ds_read_b128 v[226:229], v147 offset:53248
	ds_read_b128 v[230:233], v147 offset:54272
	ds_read_b128 v[234:237], v147 offset:55296
	ds_read_b128 v[238:241], v147 offset:56320
	global_load_lds_dwordx4 v[162:163], off
	s_add_i32 m0, s0, 0x2000
	s_add_u32 s0, s22, 0x208080
	v_lshl_add_u64 v[162:163], v[166:167], 0, s[70:71]
	s_addc_u32 s1, s23, 0
	s_add_i32 s3, s4, s11
	global_load_lds_dwordx4 v[162:163], off
	s_mov_b32 m0, s3
	s_nop 0
	global_load_lds_dwordx4 v4, s[0:1]
	s_add_i32 m0, s3, 0x2000
	s_nop 0
	global_load_lds_dwordx4 v130, s[0:1]
	v_lshl_add_u64 v[162:163], v[176:177], 0, s[70:71]
	s_mov_b32 m0, s51
	s_nop 0
	global_load_lds_dwordx4 v[162:163], off
	v_lshl_add_u64 v[162:163], v[180:181], 0, s[70:71]
	s_mov_b32 m0, s52
	s_nop 0
	global_load_lds_dwordx4 v[162:163], off
	s_waitcnt vmcnt(8) lgkmcnt(0)
	s_barrier
	v_mfma_f32_16x16x32_bf16 v[62:65], v[140:143], v[210:213], v[62:65]
	v_mfma_f32_16x16x32_bf16 v[58:61], v[172:175], v[210:213], v[58:61]
	v_mfma_f32_16x16x32_bf16 v[46:49], v[140:143], v[218:221], v[46:49]
	v_mfma_f32_16x16x32_bf16 v[42:45], v[172:175], v[218:221], v[42:45]
	v_mfma_f32_16x16x32_bf16 v[30:33], v[140:143], v[226:229], v[30:33]
	v_mfma_f32_16x16x32_bf16 v[26:29], v[172:175], v[226:229], v[26:29]
	v_mfma_f32_16x16x32_bf16 v[14:17], v[140:143], v[234:237], v[14:17]
	v_mfma_f32_16x16x32_bf16 v[10:13], v[172:175], v[234:237], v[10:13]
	v_mfma_f32_16x16x32_bf16 v[62:65], v[148:151], v[214:217], v[62:65]
	v_mfma_f32_16x16x32_bf16 v[58:61], v[190:193], v[214:217], v[58:61]
	v_mfma_f32_16x16x32_bf16 v[46:49], v[148:151], v[222:225], v[46:49]
	v_mfma_f32_16x16x32_bf16 v[42:45], v[190:193], v[222:225], v[42:45]
	v_mfma_f32_16x16x32_bf16 v[30:33], v[148:151], v[230:233], v[30:33]
	v_mfma_f32_16x16x32_bf16 v[26:29], v[190:193], v[230:233], v[26:29]
	v_mfma_f32_16x16x32_bf16 v[14:17], v[148:151], v[238:241], v[14:17]
	v_mfma_f32_16x16x32_bf16 v[10:13], v[190:193], v[238:241], v[10:13]
	v_mfma_f32_16x16x32_bf16 v[54:57], v[194:197], v[210:213], v[54:57]
	v_mfma_f32_16x16x32_bf16 v[50:53], v[202:205], v[210:213], v[50:53]
	v_mfma_f32_16x16x32_bf16 v[38:41], v[194:197], v[218:221], v[38:41]
	v_mfma_f32_16x16x32_bf16 v[34:37], v[202:205], v[218:221], v[34:37]
	v_mfma_f32_16x16x32_bf16 v[22:25], v[194:197], v[226:229], v[22:25]
	v_mfma_f32_16x16x32_bf16 v[18:21], v[202:205], v[226:229], v[18:21]
	v_mfma_f32_16x16x32_bf16 v[6:9], v[194:197], v[234:237], v[6:9]
	v_mfma_f32_16x16x32_bf16 v[0:3], v[202:205], v[234:237], v[0:3]
	v_mfma_f32_16x16x32_bf16 v[54:57], v[198:201], v[214:217], v[54:57]
	v_mfma_f32_16x16x32_bf16 v[50:53], v[206:209], v[214:217], v[50:53]
	v_mfma_f32_16x16x32_bf16 v[38:41], v[198:201], v[222:225], v[38:41]
	v_mfma_f32_16x16x32_bf16 v[34:37], v[206:209], v[222:225], v[34:37]
	v_mfma_f32_16x16x32_bf16 v[22:25], v[198:201], v[230:233], v[22:25]
	v_mfma_f32_16x16x32_bf16 v[18:21], v[206:209], v[230:233], v[18:21]
	v_mfma_f32_16x16x32_bf16 v[6:9], v[198:201], v[238:241], v[6:9]
	v_mfma_f32_16x16x32_bf16 v[0:3], v[206:209], v[238:241], v[0:3]
	s_add_i32 s9, s9, 2
	s_add_u32 s2, s2, 0x100
	s_addc_u32 s8, s8, 0
	s_cmpk_gt_u32 s9, 0x7d
	s_mov_b64 s[0:1], s[14:15]
	s_barrier
	s_cbranch_scc0 .LBB0_81
	s_and_b64 vcc, exec, s[48:49]
	s_cbranch_vccz .LBB0_84
	s_barrier

.Lpeelmid_124:
	s_add_i32 s3, 0, 0x18000
	v_add_u32_e32 v164, s3, v141
	s_add_i32 s6, 0, 0x1c000
	ds_read_b128 v[144:147], v164
	ds_read_b128 v[148:151], v164 offset:1024
	ds_read_b128 v[172:175], v164 offset:2048
	ds_read_b128 v[190:193], v164 offset:3072
	v_add_u32_e32 v164, s6, v141
	ds_read_b128 v[194:197], v164
	ds_read_b128 v[198:201], v164 offset:1024
	ds_read_b128 v[202:205], v164 offset:2048
	ds_read_b128 v[206:209], v164 offset:3072
	s_add_u32 s4, s14, 0x80000
	s_addc_u32 s5, s15, 0
	s_mov_b32 m0, s34
	ds_read_b128 v[210:213], v143 offset:32768
	ds_read_b128 v[214:217], v143 offset:33792
	ds_read_b128 v[218:221], v143 offset:34816
	ds_read_b128 v[222:225], v143 offset:35840
	ds_read_b128 v[226:229], v143 offset:36864
	ds_read_b128 v[230:233], v143 offset:37888
	ds_read_b128 v[234:237], v143 offset:38912
	ds_read_b128 v[238:241], v143 offset:39936
	global_load_lds_dwordx4 v134, s[4:5]
	v_lshl_add_u64 v[242:243], s[4:5], 0, v[132:133]
	s_mov_b32 m0, s35
	s_nop 0
	global_load_lds_dwordx4 v132, s[4:5]
	s_waitcnt vmcnt(8) lgkmcnt(0)
	s_barrier
	v_mfma_f32_16x16x32_bf16 v[126:129], v[144:147], v[210:213], v[126:129]
	v_mfma_f32_16x16x32_bf16 v[122:125], v[172:175], v[210:213], v[122:125]
	v_mfma_f32_16x16x32_bf16 v[118:121], v[144:147], v[218:221], v[118:121]
	v_mfma_f32_16x16x32_bf16 v[114:117], v[172:175], v[218:221], v[114:117]
	v_mfma_f32_16x16x32_bf16 v[110:113], v[144:147], v[226:229], v[110:113]
	v_mfma_f32_16x16x32_bf16 v[106:109], v[172:175], v[226:229], v[106:109]
	v_mfma_f32_16x16x32_bf16 v[102:105], v[144:147], v[234:237], v[102:105]
	v_mfma_f32_16x16x32_bf16 v[98:101], v[172:175], v[234:237], v[98:101]
	v_mfma_f32_16x16x32_bf16 v[126:129], v[148:151], v[214:217], v[126:129]
	v_mfma_f32_16x16x32_bf16 v[122:125], v[190:193], v[214:217], v[122:125]
	v_mfma_f32_16x16x32_bf16 v[118:121], v[148:151], v[222:225], v[118:121]
	v_mfma_f32_16x16x32_bf16 v[114:117], v[190:193], v[222:225], v[114:117]
	v_mfma_f32_16x16x32_bf16 v[110:113], v[148:151], v[230:233], v[110:113]
	v_mfma_f32_16x16x32_bf16 v[106:109], v[190:193], v[230:233], v[106:109]
	v_mfma_f32_16x16x32_bf16 v[102:105], v[148:151], v[238:241], v[102:105]
	v_mfma_f32_16x16x32_bf16 v[98:101], v[190:193], v[238:241], v[98:101]
	v_mfma_f32_16x16x32_bf16 v[70:73], v[194:197], v[210:213], v[70:73]
	v_mfma_f32_16x16x32_bf16 v[66:69], v[202:205], v[210:213], v[66:69]
	v_mfma_f32_16x16x32_bf16 v[54:57], v[194:197], v[218:221], v[54:57]
	v_mfma_f32_16x16x32_bf16 v[50:53], v[202:205], v[218:221], v[50:53]
	v_mfma_f32_16x16x32_bf16 v[46:49], v[194:197], v[226:229], v[46:49]
	v_mfma_f32_16x16x32_bf16 v[42:45], v[202:205], v[226:229], v[42:45]
	v_mfma_f32_16x16x32_bf16 v[38:41], v[194:197], v[234:237], v[38:41]
	v_mfma_f32_16x16x32_bf16 v[34:37], v[202:205], v[234:237], v[34:37]
	v_mfma_f32_16x16x32_bf16 v[70:73], v[198:201], v[214:217], v[70:73]
	v_mfma_f32_16x16x32_bf16 v[66:69], v[206:209], v[214:217], v[66:69]
	v_mfma_f32_16x16x32_bf16 v[54:57], v[198:201], v[222:225], v[54:57]
	v_mfma_f32_16x16x32_bf16 v[50:53], v[206:209], v[222:225], v[50:53]
	v_mfma_f32_16x16x32_bf16 v[46:49], v[198:201], v[230:233], v[46:49]
	v_mfma_f32_16x16x32_bf16 v[42:45], v[206:209], v[230:233], v[42:45]
	v_mfma_f32_16x16x32_bf16 v[38:41], v[198:201], v[238:241], v[38:41]
	v_mfma_f32_16x16x32_bf16 v[34:37], v[206:209], v[238:241], v[34:37]
	s_barrier
	s_add_i32 s3, s3, s27
	v_lshl_add_u64 v[162:163], v[162:163], 0, s[70:71]
	s_mov_b32 m0, s3
	ds_read_b128 v[210:213], v143 offset:49152
	ds_read_b128 v[214:217], v143 offset:50176
	ds_read_b128 v[218:221], v143 offset:51200
	ds_read_b128 v[222:225], v143 offset:52224
	ds_read_b128 v[226:229], v143 offset:53248
	ds_read_b128 v[230:233], v143 offset:54272
	ds_read_b128 v[234:237], v143 offset:55296
	ds_read_b128 v[238:241], v143 offset:56320
	global_load_lds_dwordx4 v[162:163], off
	s_add_i32 m0, s3, 0x2000
	s_add_u32 s0, s0, 0x80080
	v_lshl_add_u64 v[162:163], v[166:167], 0, s[70:71]
	s_addc_u32 s1, s1, 0
	s_add_i32 s3, s6, s27
	global_load_lds_dwordx4 v[162:163], off
	s_mov_b32 m0, s3
	s_nop 0
	global_load_lds_dwordx4 v4, s[0:1]
	s_add_i32 m0, s3, 0x2000
	s_nop 0
	global_load_lds_dwordx4 v130, s[0:1]
	v_lshl_add_u64 v[162:163], v[176:177], 0, s[70:71]
	s_mov_b32 m0, s36
	s_nop 0
	global_load_lds_dwordx4 v[162:163], off
	v_lshl_add_u64 v[162:163], v[180:181], 0, s[70:71]
	s_mov_b32 m0, s37
	s_nop 0
	global_load_lds_dwordx4 v[162:163], off
	s_waitcnt vmcnt(8) lgkmcnt(0)
	s_barrier
	v_mfma_f32_16x16x32_bf16 v[94:97], v[144:147], v[210:213], v[94:97]
	v_mfma_f32_16x16x32_bf16 v[90:93], v[172:175], v[210:213], v[90:93]
	v_mfma_f32_16x16x32_bf16 v[86:89], v[144:147], v[218:221], v[86:89]
	v_mfma_f32_16x16x32_bf16 v[82:85], v[172:175], v[218:221], v[82:85]
	v_mfma_f32_16x16x32_bf16 v[78:81], v[144:147], v[226:229], v[78:81]
	v_mfma_f32_16x16x32_bf16 v[74:77], v[172:175], v[226:229], v[74:77]
	v_mfma_f32_16x16x32_bf16 v[62:65], v[144:147], v[234:237], v[62:65]
	v_mfma_f32_16x16x32_bf16 v[58:61], v[172:175], v[234:237], v[58:61]
	v_mfma_f32_16x16x32_bf16 v[94:97], v[148:151], v[214:217], v[94:97]
	v_mfma_f32_16x16x32_bf16 v[90:93], v[190:193], v[214:217], v[90:93]
	v_mfma_f32_16x16x32_bf16 v[86:89], v[148:151], v[222:225], v[86:89]
	v_mfma_f32_16x16x32_bf16 v[82:85], v[190:193], v[222:225], v[82:85]
	v_mfma_f32_16x16x32_bf16 v[78:81], v[148:151], v[230:233], v[78:81]
	v_mfma_f32_16x16x32_bf16 v[74:77], v[190:193], v[230:233], v[74:77]
	v_mfma_f32_16x16x32_bf16 v[62:65], v[148:151], v[238:241], v[62:65]
	v_mfma_f32_16x16x32_bf16 v[58:61], v[190:193], v[238:241], v[58:61]
	v_mfma_f32_16x16x32_bf16 v[30:33], v[194:197], v[210:213], v[30:33]
	v_mfma_f32_16x16x32_bf16 v[26:29], v[202:205], v[210:213], v[26:29]
	v_mfma_f32_16x16x32_bf16 v[22:25], v[194:197], v[218:221], v[22:25]
	v_mfma_f32_16x16x32_bf16 v[18:21], v[202:205], v[218:221], v[18:21]
	v_mfma_f32_16x16x32_bf16 v[14:17], v[194:197], v[226:229], v[14:17]
	v_mfma_f32_16x16x32_bf16 v[10:13], v[202:205], v[226:229], v[10:13]
	v_mfma_f32_16x16x32_bf16 v[6:9], v[194:197], v[234:237], v[6:9]
	v_mfma_f32_16x16x32_bf16 v[0:3], v[202:205], v[234:237], v[0:3]
	v_mfma_f32_16x16x32_bf16 v[30:33], v[198:201], v[214:217], v[30:33]
	v_mfma_f32_16x16x32_bf16 v[26:29], v[206:209], v[214:217], v[26:29]
	v_mfma_f32_16x16x32_bf16 v[22:25], v[198:201], v[222:225], v[22:25]
	v_mfma_f32_16x16x32_bf16 v[18:21], v[206:209], v[222:225], v[18:21]
	v_mfma_f32_16x16x32_bf16 v[14:17], v[198:201], v[230:233], v[14:17]
	v_mfma_f32_16x16x32_bf16 v[10:13], v[206:209], v[230:233], v[10:13]
	v_mfma_f32_16x16x32_bf16 v[6:9], v[198:201], v[238:241], v[6:9]
	v_mfma_f32_16x16x32_bf16 v[0:3], v[206:209], v[238:241], v[0:3]
	s_add_i32 s28, s28, 2
	s_add_u32 s22, s22, 0x100
	s_addc_u32 s23, s23, 0
	s_add_u32 s9, s9, 0x100
	s_addc_u32 s25, s25, 0
	s_cmp_gt_u32 s28, 29
	s_barrier
	s_cbranch_scc0 .LBB0_124
	s_and_b64 vcc, exec, s[42:43]
	s_cbranch_vccz .LBB0_127
	s_barrier

.Lpeelmid_163:
	s_add_i32 s3, 0, 0x18000
	v_add_u32_e32 v164, s3, v145
	s_add_i32 s6, 0, 0x1c000
	ds_read_b128 v[140:143], v164
	ds_read_b128 v[148:151], v164 offset:1024
	ds_read_b128 v[172:175], v164 offset:2048
	ds_read_b128 v[190:193], v164 offset:3072
	v_add_u32_e32 v164, s6, v145
	ds_read_b128 v[194:197], v164
	ds_read_b128 v[198:201], v164 offset:1024
	ds_read_b128 v[202:205], v164 offset:2048
	ds_read_b128 v[206:209], v164 offset:3072
	s_add_u32 s4, s14, 0x80000
	s_addc_u32 s5, s15, 0
	s_mov_b32 m0, s30
	ds_read_b128 v[210:213], v147 offset:32768
	ds_read_b128 v[214:217], v147 offset:33792
	ds_read_b128 v[218:221], v147 offset:34816
	ds_read_b128 v[222:225], v147 offset:35840
	ds_read_b128 v[226:229], v147 offset:36864
	ds_read_b128 v[230:233], v147 offset:37888
	ds_read_b128 v[234:237], v147 offset:38912
	ds_read_b128 v[238:241], v147 offset:39936
	global_load_lds_dwordx4 v134, s[4:5]
	v_lshl_add_u64 v[242:243], s[4:5], 0, v[132:133]
	s_mov_b32 m0, s31
	s_nop 0
	global_load_lds_dwordx4 v132, s[4:5]
	s_waitcnt vmcnt(8) lgkmcnt(0)
	s_barrier
	v_mfma_f32_16x16x32_bf16 v[126:129], v[140:143], v[210:213], v[126:129]
	v_mfma_f32_16x16x32_bf16 v[122:125], v[172:175], v[210:213], v[122:125]
	v_mfma_f32_16x16x32_bf16 v[110:113], v[140:143], v[218:221], v[110:113]
	v_mfma_f32_16x16x32_bf16 v[106:109], v[172:175], v[218:221], v[106:109]
	v_mfma_f32_16x16x32_bf16 v[94:97], v[140:143], v[226:229], v[94:97]
	v_mfma_f32_16x16x32_bf16 v[90:93], v[172:175], v[226:229], v[90:93]
	v_mfma_f32_16x16x32_bf16 v[78:81], v[140:143], v[234:237], v[78:81]
	v_mfma_f32_16x16x32_bf16 v[74:77], v[172:175], v[234:237], v[74:77]
	v_mfma_f32_16x16x32_bf16 v[126:129], v[148:151], v[214:217], v[126:129]
	v_mfma_f32_16x16x32_bf16 v[122:125], v[190:193], v[214:217], v[122:125]
	v_mfma_f32_16x16x32_bf16 v[110:113], v[148:151], v[222:225], v[110:113]
	v_mfma_f32_16x16x32_bf16 v[106:109], v[190:193], v[222:225], v[106:109]
	v_mfma_f32_16x16x32_bf16 v[94:97], v[148:151], v[230:233], v[94:97]
	v_mfma_f32_16x16x32_bf16 v[90:93], v[190:193], v[230:233], v[90:93]
	v_mfma_f32_16x16x32_bf16 v[78:81], v[148:151], v[238:241], v[78:81]
	v_mfma_f32_16x16x32_bf16 v[74:77], v[190:193], v[238:241], v[74:77]
	v_mfma_f32_16x16x32_bf16 v[118:121], v[194:197], v[210:213], v[118:121]
	v_mfma_f32_16x16x32_bf16 v[114:117], v[202:205], v[210:213], v[114:117]
	v_mfma_f32_16x16x32_bf16 v[102:105], v[194:197], v[218:221], v[102:105]
	v_mfma_f32_16x16x32_bf16 v[98:101], v[202:205], v[218:221], v[98:101]
	v_mfma_f32_16x16x32_bf16 v[86:89], v[194:197], v[226:229], v[86:89]
	v_mfma_f32_16x16x32_bf16 v[82:85], v[202:205], v[226:229], v[82:85]
	v_mfma_f32_16x16x32_bf16 v[70:73], v[194:197], v[234:237], v[70:73]
	v_mfma_f32_16x16x32_bf16 v[66:69], v[202:205], v[234:237], v[66:69]
	v_mfma_f32_16x16x32_bf16 v[118:121], v[198:201], v[214:217], v[118:121]
	v_mfma_f32_16x16x32_bf16 v[114:117], v[206:209], v[214:217], v[114:117]
	v_mfma_f32_16x16x32_bf16 v[102:105], v[198:201], v[222:225], v[102:105]
	v_mfma_f32_16x16x32_bf16 v[98:101], v[206:209], v[222:225], v[98:101]
	v_mfma_f32_16x16x32_bf16 v[86:89], v[198:201], v[230:233], v[86:89]
	v_mfma_f32_16x16x32_bf16 v[82:85], v[206:209], v[230:233], v[82:85]
	v_mfma_f32_16x16x32_bf16 v[70:73], v[198:201], v[238:241], v[70:73]
	v_mfma_f32_16x16x32_bf16 v[66:69], v[206:209], v[238:241], v[66:69]
	s_barrier
	s_add_i32 s3, s3, s11
	v_lshl_add_u64 v[162:163], v[162:163], 0, s[70:71]
	s_mov_b32 m0, s3
	ds_read_b128 v[210:213], v147 offset:49152
	ds_read_b128 v[214:217], v147 offset:50176
	ds_read_b128 v[218:221], v147 offset:51200
	ds_read_b128 v[222:225], v147 offset:52224
	ds_read_b128 v[226:229], v147 offset:53248
	ds_read_b128 v[230:233], v147 offset:54272
	ds_read_b128 v[234:237], v147 offset:55296
	ds_read_b128 v[238:241], v147 offset:56320
	global_load_lds_dwordx4 v[162:163], off
	s_add_i32 m0, s3, 0x2000
	s_add_u32 s0, s0, 0x80080
	v_lshl_add_u64 v[162:163], v[166:167], 0, s[70:71]
	s_addc_u32 s1, s1, 0
	s_add_i32 s3, s6, s11
	global_load_lds_dwordx4 v[162:163], off
	s_mov_b32 m0, s3
	s_nop 0
	global_load_lds_dwordx4 v4, s[0:1]
	s_add_i32 m0, s3, 0x2000
	s_nop 0
	global_load_lds_dwordx4 v130, s[0:1]
	v_lshl_add_u64 v[162:163], v[176:177], 0, s[70:71]
	s_mov_b32 m0, s35
	s_nop 0
	global_load_lds_dwordx4 v[162:163], off
	v_lshl_add_u64 v[162:163], v[180:181], 0, s[70:71]
	s_mov_b32 m0, s36
	s_nop 0
	global_load_lds_dwordx4 v[162:163], off
	s_waitcnt vmcnt(8) lgkmcnt(0)
	s_barrier
	v_mfma_f32_16x16x32_bf16 v[62:65], v[140:143], v[210:213], v[62:65]
	v_mfma_f32_16x16x32_bf16 v[58:61], v[172:175], v[210:213], v[58:61]
	v_mfma_f32_16x16x32_bf16 v[46:49], v[140:143], v[218:221], v[46:49]
	v_mfma_f32_16x16x32_bf16 v[42:45], v[172:175], v[218:221], v[42:45]
	v_mfma_f32_16x16x32_bf16 v[30:33], v[140:143], v[226:229], v[30:33]
	v_mfma_f32_16x16x32_bf16 v[26:29], v[172:175], v[226:229], v[26:29]
	v_mfma_f32_16x16x32_bf16 v[14:17], v[140:143], v[234:237], v[14:17]
	v_mfma_f32_16x16x32_bf16 v[10:13], v[172:175], v[234:237], v[10:13]
	v_mfma_f32_16x16x32_bf16 v[62:65], v[148:151], v[214:217], v[62:65]
	v_mfma_f32_16x16x32_bf16 v[58:61], v[190:193], v[214:217], v[58:61]
	v_mfma_f32_16x16x32_bf16 v[46:49], v[148:151], v[222:225], v[46:49]
	v_mfma_f32_16x16x32_bf16 v[42:45], v[190:193], v[222:225], v[42:45]
	v_mfma_f32_16x16x32_bf16 v[30:33], v[148:151], v[230:233], v[30:33]
	v_mfma_f32_16x16x32_bf16 v[26:29], v[190:193], v[230:233], v[26:29]
	v_mfma_f32_16x16x32_bf16 v[14:17], v[148:151], v[238:241], v[14:17]
	v_mfma_f32_16x16x32_bf16 v[10:13], v[190:193], v[238:241], v[10:13]
	v_mfma_f32_16x16x32_bf16 v[54:57], v[194:197], v[210:213], v[54:57]
	v_mfma_f32_16x16x32_bf16 v[50:53], v[202:205], v[210:213], v[50:53]
	v_mfma_f32_16x16x32_bf16 v[38:41], v[194:197], v[218:221], v[38:41]
	v_mfma_f32_16x16x32_bf16 v[34:37], v[202:205], v[218:221], v[34:37]
	v_mfma_f32_16x16x32_bf16 v[22:25], v[194:197], v[226:229], v[22:25]
	v_mfma_f32_16x16x32_bf16 v[18:21], v[202:205], v[226:229], v[18:21]
	v_mfma_f32_16x16x32_bf16 v[6:9], v[194:197], v[234:237], v[6:9]
	v_mfma_f32_16x16x32_bf16 v[0:3], v[202:205], v[234:237], v[0:3]
	v_mfma_f32_16x16x32_bf16 v[54:57], v[198:201], v[214:217], v[54:57]
	v_mfma_f32_16x16x32_bf16 v[50:53], v[206:209], v[214:217], v[50:53]
	v_mfma_f32_16x16x32_bf16 v[38:41], v[198:201], v[222:225], v[38:41]
	v_mfma_f32_16x16x32_bf16 v[34:37], v[206:209], v[222:225], v[34:37]
	v_mfma_f32_16x16x32_bf16 v[22:25], v[198:201], v[230:233], v[22:25]
	v_mfma_f32_16x16x32_bf16 v[18:21], v[206:209], v[230:233], v[18:21]
	v_mfma_f32_16x16x32_bf16 v[6:9], v[198:201], v[238:241], v[6:9]
	v_mfma_f32_16x16x32_bf16 v[0:3], v[206:209], v[238:241], v[0:3]
	s_add_i32 s24, s24, 2
	s_add_u32 s22, s22, 0x100
	s_addc_u32 s23, s23, 0
	s_add_u32 s9, s9, 0x100
	s_addc_u32 s10, s10, 0
	s_cmp_gt_u32 s24, 29
	s_barrier
	s_cbranch_scc0 .LBB0_163
	s_and_b64 vcc, exec, s[46:47]
	s_cbranch_vccz .LBB0_166
	s_barrier

.Lpeelmid_205:
	s_add_i32 s3, 0, 0x18000
	v_add_u32_e32 v173, s3, v168
	s_add_i32 s6, 0, 0x1c000
	ds_read_b128 v[140:143], v173
	ds_read_b128 v[174:177], v173 offset:1024
	ds_read_b128 v[190:193], v173 offset:2048
	ds_read_b128 v[194:197], v173 offset:3072
	v_add_u32_e32 v173, s6, v168
	ds_read_b128 v[198:201], v173
	ds_read_b128 v[202:205], v173 offset:1024
	ds_read_b128 v[206:209], v173 offset:2048
	ds_read_b128 v[210:213], v173 offset:3072
	s_add_u32 s4, s14, 0x40000
	s_addc_u32 s5, s15, 0
	s_mov_b32 m0, s31
	ds_read_b128 v[214:217], v172 offset:32768
	ds_read_b128 v[218:221], v172 offset:33792
	ds_read_b128 v[222:225], v172 offset:34816
	ds_read_b128 v[226:229], v172 offset:35840
	ds_read_b128 v[230:233], v172 offset:36864
	ds_read_b128 v[234:237], v172 offset:37888
	ds_read_b128 v[238:241], v172 offset:38912
	ds_read_b128 v[242:245], v172 offset:39936
	global_load_lds_dwordx4 v130, s[4:5]
	v_lshl_add_u64 v[180:181], s[4:5], 0, v[132:133]
	s_mov_b32 m0, s34
	s_nop 0
	global_load_lds_dwordx4 v132, s[4:5]
	s_waitcnt vmcnt(8) lgkmcnt(0)
	s_barrier
	v_mfma_f32_16x16x32_bf16 v[126:129], v[140:143], v[214:217], v[126:129]
	v_mfma_f32_16x16x32_bf16 v[122:125], v[190:193], v[214:217], v[122:125]
	v_mfma_f32_16x16x32_bf16 v[118:121], v[140:143], v[222:225], v[118:121]
	v_mfma_f32_16x16x32_bf16 v[114:117], v[190:193], v[222:225], v[114:117]
	v_mfma_f32_16x16x32_bf16 v[110:113], v[140:143], v[230:233], v[110:113]
	v_mfma_f32_16x16x32_bf16 v[106:109], v[190:193], v[230:233], v[106:109]
	v_mfma_f32_16x16x32_bf16 v[102:105], v[140:143], v[238:241], v[102:105]
	v_mfma_f32_16x16x32_bf16 v[98:101], v[190:193], v[238:241], v[98:101]
	v_mfma_f32_16x16x32_bf16 v[126:129], v[174:177], v[218:221], v[126:129]
	v_mfma_f32_16x16x32_bf16 v[122:125], v[194:197], v[218:221], v[122:125]
	v_mfma_f32_16x16x32_bf16 v[118:121], v[174:177], v[226:229], v[118:121]
	v_mfma_f32_16x16x32_bf16 v[114:117], v[194:197], v[226:229], v[114:117]
	v_mfma_f32_16x16x32_bf16 v[110:113], v[174:177], v[234:237], v[110:113]
	v_mfma_f32_16x16x32_bf16 v[106:109], v[194:197], v[234:237], v[106:109]
	v_mfma_f32_16x16x32_bf16 v[102:105], v[174:177], v[242:245], v[102:105]
	v_mfma_f32_16x16x32_bf16 v[98:101], v[194:197], v[242:245], v[98:101]
	v_mfma_f32_16x16x32_bf16 v[62:65], v[198:201], v[214:217], v[62:65]
	v_mfma_f32_16x16x32_bf16 v[58:61], v[206:209], v[214:217], v[58:61]
	v_mfma_f32_16x16x32_bf16 v[54:57], v[198:201], v[222:225], v[54:57]
	v_mfma_f32_16x16x32_bf16 v[50:53], v[206:209], v[222:225], v[50:53]
	v_mfma_f32_16x16x32_bf16 v[46:49], v[198:201], v[230:233], v[46:49]
	v_mfma_f32_16x16x32_bf16 v[42:45], v[206:209], v[230:233], v[42:45]
	v_mfma_f32_16x16x32_bf16 v[38:41], v[198:201], v[238:241], v[38:41]
	v_mfma_f32_16x16x32_bf16 v[34:37], v[206:209], v[238:241], v[34:37]
	v_mfma_f32_16x16x32_bf16 v[62:65], v[202:205], v[218:221], v[62:65]
	v_mfma_f32_16x16x32_bf16 v[58:61], v[210:213], v[218:221], v[58:61]
	v_mfma_f32_16x16x32_bf16 v[54:57], v[202:205], v[226:229], v[54:57]
	v_mfma_f32_16x16x32_bf16 v[50:53], v[210:213], v[226:229], v[50:53]
	v_mfma_f32_16x16x32_bf16 v[46:49], v[202:205], v[234:237], v[46:49]
	v_mfma_f32_16x16x32_bf16 v[42:45], v[210:213], v[234:237], v[42:45]
	v_mfma_f32_16x16x32_bf16 v[38:41], v[202:205], v[242:245], v[38:41]
	v_mfma_f32_16x16x32_bf16 v[34:37], v[210:213], v[242:245], v[34:37]
	s_barrier
	s_add_i32 s3, s3, s26
	v_lshl_add_u64 v[144:145], v[144:145], 0, s[70:71]
	s_mov_b32 m0, s3
	ds_read_b128 v[214:217], v172 offset:49152
	ds_read_b128 v[218:221], v172 offset:50176
	ds_read_b128 v[222:225], v172 offset:51200
	ds_read_b128 v[226:229], v172 offset:52224
	ds_read_b128 v[230:233], v172 offset:53248
	ds_read_b128 v[234:237], v172 offset:54272
	ds_read_b128 v[238:241], v172 offset:55296
	ds_read_b128 v[242:245], v172 offset:56320
	global_load_lds_dwordx4 v[144:145], off
	s_add_i32 m0, s3, 0x2000
	s_add_u32 s0, s0, 0x40080
	v_lshl_add_u64 v[144:145], v[246:247], 0, s[70:71]
	s_addc_u32 s1, s1, 0
	s_add_i32 s3, s6, s26
	global_load_lds_dwordx4 v[144:145], off
	s_mov_b32 m0, s3
	s_nop 0
	global_load_lds_dwordx4 v4, s[0:1]
	s_add_i32 m0, s3, 0x2000
	s_nop 0
	global_load_lds_dwordx4 v134, s[0:1]
	v_lshl_add_u64 v[144:145], v[248:249], 0, s[70:71]
	s_mov_b32 m0, s35
	s_nop 0
	global_load_lds_dwordx4 v[144:145], off
	v_lshl_add_u64 v[144:145], v[250:251], 0, s[70:71]
	s_mov_b32 m0, s36
	s_nop 0
	global_load_lds_dwordx4 v[144:145], off
	s_waitcnt vmcnt(8) lgkmcnt(0)
	s_barrier
	v_mfma_f32_16x16x32_bf16 v[94:97], v[140:143], v[214:217], v[94:97]
	v_mfma_f32_16x16x32_bf16 v[90:93], v[190:193], v[214:217], v[90:93]
	v_mfma_f32_16x16x32_bf16 v[86:89], v[140:143], v[222:225], v[86:89]
	v_mfma_f32_16x16x32_bf16 v[82:85], v[190:193], v[222:225], v[82:85]
	v_mfma_f32_16x16x32_bf16 v[78:81], v[140:143], v[230:233], v[78:81]
	v_mfma_f32_16x16x32_bf16 v[74:77], v[190:193], v[230:233], v[74:77]
	v_mfma_f32_16x16x32_bf16 v[70:73], v[140:143], v[238:241], v[70:73]
	v_mfma_f32_16x16x32_bf16 v[66:69], v[190:193], v[238:241], v[66:69]
	v_mfma_f32_16x16x32_bf16 v[94:97], v[174:177], v[218:221], v[94:97]
	v_mfma_f32_16x16x32_bf16 v[90:93], v[194:197], v[218:221], v[90:93]
	v_mfma_f32_16x16x32_bf16 v[86:89], v[174:177], v[226:229], v[86:89]
	v_mfma_f32_16x16x32_bf16 v[82:85], v[194:197], v[226:229], v[82:85]
	v_mfma_f32_16x16x32_bf16 v[78:81], v[174:177], v[234:237], v[78:81]
	v_mfma_f32_16x16x32_bf16 v[74:77], v[194:197], v[234:237], v[74:77]
	v_mfma_f32_16x16x32_bf16 v[70:73], v[174:177], v[242:245], v[70:73]
	v_mfma_f32_16x16x32_bf16 v[66:69], v[194:197], v[242:245], v[66:69]
	v_mfma_f32_16x16x32_bf16 v[30:33], v[198:201], v[214:217], v[30:33]
	v_mfma_f32_16x16x32_bf16 v[26:29], v[206:209], v[214:217], v[26:29]
	v_mfma_f32_16x16x32_bf16 v[22:25], v[198:201], v[222:225], v[22:25]
	v_mfma_f32_16x16x32_bf16 v[18:21], v[206:209], v[222:225], v[18:21]
	v_mfma_f32_16x16x32_bf16 v[14:17], v[198:201], v[230:233], v[14:17]
	v_mfma_f32_16x16x32_bf16 v[10:13], v[206:209], v[230:233], v[10:13]
	v_mfma_f32_16x16x32_bf16 v[6:9], v[198:201], v[238:241], v[6:9]
	v_mfma_f32_16x16x32_bf16 v[0:3], v[206:209], v[238:241], v[0:3]
	v_mfma_f32_16x16x32_bf16 v[30:33], v[202:205], v[218:221], v[30:33]
	v_mfma_f32_16x16x32_bf16 v[26:29], v[210:213], v[218:221], v[26:29]
	v_mfma_f32_16x16x32_bf16 v[22:25], v[202:205], v[226:229], v[22:25]
	v_mfma_f32_16x16x32_bf16 v[18:21], v[210:213], v[226:229], v[18:21]
	v_mfma_f32_16x16x32_bf16 v[14:17], v[202:205], v[234:237], v[14:17]
	v_mfma_f32_16x16x32_bf16 v[10:13], v[210:213], v[234:237], v[10:13]
	v_mfma_f32_16x16x32_bf16 v[6:9], v[202:205], v[242:245], v[6:9]
	v_mfma_f32_16x16x32_bf16 v[0:3], v[210:213], v[242:245], v[0:3]
	s_add_i32 s24, s24, 2
	s_add_u32 s22, s22, 0x100
	s_addc_u32 s23, s23, 0
	s_add_u32 s9, s9, 0x100
	s_addc_u32 s10, s10, 0
	s_cmp_gt_u32 s24, 13
	s_barrier
	s_cbranch_scc0 .LBB0_205
	s_and_b64 vcc, exec, s[46:47]
	s_cbranch_vccz .LBB0_208
	s_barrier

.Lpeelmid_228:
	s_add_i32 s3, 0, 0x18000
	v_add_u32_e32 v164, s3, v149
	s_add_i32 s6, 0, 0x1c000
	ds_read_b128 v[140:143], v164
	ds_read_b128 v[144:147], v164 offset:1024
	ds_read_b128 v[172:175], v164 offset:2048
	ds_read_b128 v[190:193], v164 offset:3072
	v_add_u32_e32 v164, s6, v149
	ds_read_b128 v[194:197], v164
	ds_read_b128 v[198:201], v164 offset:1024
	ds_read_b128 v[202:205], v164 offset:2048
	ds_read_b128 v[206:209], v164 offset:3072
	s_add_u32 s4, s14, 0x40000
	s_addc_u32 s5, s15, 0
	s_mov_b32 m0, s31
	ds_read_b128 v[210:213], v151 offset:32768
	ds_read_b128 v[214:217], v151 offset:33792
	ds_read_b128 v[218:221], v151 offset:34816
	ds_read_b128 v[222:225], v151 offset:35840
	ds_read_b128 v[226:229], v151 offset:36864
	ds_read_b128 v[230:233], v151 offset:37888
	ds_read_b128 v[234:237], v151 offset:38912
	ds_read_b128 v[238:241], v151 offset:39936
	global_load_lds_dwordx4 v130, s[4:5]
	v_lshl_add_u64 v[242:243], s[4:5], 0, v[132:133]
	s_mov_b32 m0, s34
	s_nop 0
	global_load_lds_dwordx4 v132, s[4:5]
	s_waitcnt vmcnt(8) lgkmcnt(0)
	s_barrier
	v_mfma_f32_16x16x32_bf16 v[126:129], v[140:143], v[210:213], v[126:129]
	v_mfma_f32_16x16x32_bf16 v[122:125], v[172:175], v[210:213], v[122:125]
	v_mfma_f32_16x16x32_bf16 v[118:121], v[140:143], v[218:221], v[118:121]
	v_mfma_f32_16x16x32_bf16 v[114:117], v[172:175], v[218:221], v[114:117]
	v_mfma_f32_16x16x32_bf16 v[110:113], v[140:143], v[226:229], v[110:113]
	v_mfma_f32_16x16x32_bf16 v[106:109], v[172:175], v[226:229], v[106:109]
	v_mfma_f32_16x16x32_bf16 v[102:105], v[140:143], v[234:237], v[102:105]
	v_mfma_f32_16x16x32_bf16 v[98:101], v[172:175], v[234:237], v[98:101]
	v_mfma_f32_16x16x32_bf16 v[126:129], v[144:147], v[214:217], v[126:129]
	v_mfma_f32_16x16x32_bf16 v[122:125], v[190:193], v[214:217], v[122:125]
	v_mfma_f32_16x16x32_bf16 v[118:121], v[144:147], v[222:225], v[118:121]
	v_mfma_f32_16x16x32_bf16 v[114:117], v[190:193], v[222:225], v[114:117]
	v_mfma_f32_16x16x32_bf16 v[110:113], v[144:147], v[230:233], v[110:113]
	v_mfma_f32_16x16x32_bf16 v[106:109], v[190:193], v[230:233], v[106:109]
	v_mfma_f32_16x16x32_bf16 v[102:105], v[144:147], v[238:241], v[102:105]
	v_mfma_f32_16x16x32_bf16 v[98:101], v[190:193], v[238:241], v[98:101]
	v_mfma_f32_16x16x32_bf16 v[66:69], v[194:197], v[210:213], v[66:69]
	v_mfma_f32_16x16x32_bf16 v[58:61], v[202:205], v[210:213], v[58:61]
	v_mfma_f32_16x16x32_bf16 v[54:57], v[194:197], v[218:221], v[54:57]
	v_mfma_f32_16x16x32_bf16 v[50:53], v[202:205], v[218:221], v[50:53]
	v_mfma_f32_16x16x32_bf16 v[46:49], v[194:197], v[226:229], v[46:49]
	v_mfma_f32_16x16x32_bf16 v[42:45], v[202:205], v[226:229], v[42:45]
	v_mfma_f32_16x16x32_bf16 v[38:41], v[194:197], v[234:237], v[38:41]
	v_mfma_f32_16x16x32_bf16 v[34:37], v[202:205], v[234:237], v[34:37]
	v_mfma_f32_16x16x32_bf16 v[66:69], v[198:201], v[214:217], v[66:69]
	v_mfma_f32_16x16x32_bf16 v[58:61], v[206:209], v[214:217], v[58:61]
	v_mfma_f32_16x16x32_bf16 v[54:57], v[198:201], v[222:225], v[54:57]
	v_mfma_f32_16x16x32_bf16 v[50:53], v[206:209], v[222:225], v[50:53]
	v_mfma_f32_16x16x32_bf16 v[46:49], v[198:201], v[230:233], v[46:49]
	v_mfma_f32_16x16x32_bf16 v[42:45], v[206:209], v[230:233], v[42:45]
	v_mfma_f32_16x16x32_bf16 v[38:41], v[198:201], v[238:241], v[38:41]
	v_mfma_f32_16x16x32_bf16 v[34:37], v[206:209], v[238:241], v[34:37]
	s_barrier
	s_add_i32 s3, s3, s26
	v_lshl_add_u64 v[162:163], v[162:163], 0, s[70:71]
	s_mov_b32 m0, s3
	ds_read_b128 v[210:213], v151 offset:49152
	ds_read_b128 v[214:217], v151 offset:50176
	ds_read_b128 v[218:221], v151 offset:51200
	ds_read_b128 v[222:225], v151 offset:52224
	ds_read_b128 v[226:229], v151 offset:53248
	ds_read_b128 v[230:233], v151 offset:54272
	ds_read_b128 v[234:237], v151 offset:55296
	ds_read_b128 v[238:241], v151 offset:56320
	global_load_lds_dwordx4 v[162:163], off
	s_add_i32 m0, s3, 0x2000
	s_add_u32 s0, s0, 0x40080
	v_lshl_add_u64 v[162:163], v[166:167], 0, s[70:71]
	s_addc_u32 s1, s1, 0
	s_add_i32 s3, s6, s26
	global_load_lds_dwordx4 v[162:163], off
	s_mov_b32 m0, s3
	s_nop 0
	global_load_lds_dwordx4 v4, s[0:1]
	s_add_i32 m0, s3, 0x2000
	s_nop 0
	global_load_lds_dwordx4 v134, s[0:1]
	v_lshl_add_u64 v[162:163], v[176:177], 0, s[70:71]
	s_mov_b32 m0, s35
	s_nop 0
	global_load_lds_dwordx4 v[162:163], off
	v_lshl_add_u64 v[162:163], v[180:181], 0, s[70:71]
	s_mov_b32 m0, s36
	s_nop 0
	global_load_lds_dwordx4 v[162:163], off
	s_waitcnt vmcnt(8) lgkmcnt(0)
	s_barrier
	v_mfma_f32_16x16x32_bf16 v[94:97], v[140:143], v[210:213], v[94:97]
	v_mfma_f32_16x16x32_bf16 v[90:93], v[172:175], v[210:213], v[90:93]
	v_mfma_f32_16x16x32_bf16 v[86:89], v[140:143], v[218:221], v[86:89]
	v_mfma_f32_16x16x32_bf16 v[82:85], v[172:175], v[218:221], v[82:85]
	v_mfma_f32_16x16x32_bf16 v[78:81], v[140:143], v[226:229], v[78:81]
	v_mfma_f32_16x16x32_bf16 v[74:77], v[172:175], v[226:229], v[74:77]
	v_mfma_f32_16x16x32_bf16 v[70:73], v[140:143], v[234:237], v[70:73]
	v_mfma_f32_16x16x32_bf16 v[62:65], v[172:175], v[234:237], v[62:65]
	v_mfma_f32_16x16x32_bf16 v[94:97], v[144:147], v[214:217], v[94:97]
	v_mfma_f32_16x16x32_bf16 v[90:93], v[190:193], v[214:217], v[90:93]
	v_mfma_f32_16x16x32_bf16 v[86:89], v[144:147], v[222:225], v[86:89]
	v_mfma_f32_16x16x32_bf16 v[82:85], v[190:193], v[222:225], v[82:85]
	v_mfma_f32_16x16x32_bf16 v[78:81], v[144:147], v[230:233], v[78:81]
	v_mfma_f32_16x16x32_bf16 v[74:77], v[190:193], v[230:233], v[74:77]
	v_mfma_f32_16x16x32_bf16 v[70:73], v[144:147], v[238:241], v[70:73]
	v_mfma_f32_16x16x32_bf16 v[62:65], v[190:193], v[238:241], v[62:65]
	v_mfma_f32_16x16x32_bf16 v[30:33], v[194:197], v[210:213], v[30:33]
	v_mfma_f32_16x16x32_bf16 v[26:29], v[202:205], v[210:213], v[26:29]
	v_mfma_f32_16x16x32_bf16 v[22:25], v[194:197], v[218:221], v[22:25]
	v_mfma_f32_16x16x32_bf16 v[18:21], v[202:205], v[218:221], v[18:21]
	v_mfma_f32_16x16x32_bf16 v[14:17], v[194:197], v[226:229], v[14:17]
	v_mfma_f32_16x16x32_bf16 v[10:13], v[202:205], v[226:229], v[10:13]
	v_mfma_f32_16x16x32_bf16 v[6:9], v[194:197], v[234:237], v[6:9]
	v_mfma_f32_16x16x32_bf16 v[0:3], v[202:205], v[234:237], v[0:3]
	v_mfma_f32_16x16x32_bf16 v[30:33], v[198:201], v[214:217], v[30:33]
	v_mfma_f32_16x16x32_bf16 v[26:29], v[206:209], v[214:217], v[26:29]
	v_mfma_f32_16x16x32_bf16 v[22:25], v[198:201], v[222:225], v[22:25]
	v_mfma_f32_16x16x32_bf16 v[18:21], v[206:209], v[222:225], v[18:21]
	v_mfma_f32_16x16x32_bf16 v[14:17], v[198:201], v[230:233], v[14:17]
	v_mfma_f32_16x16x32_bf16 v[10:13], v[206:209], v[230:233], v[10:13]
	v_mfma_f32_16x16x32_bf16 v[6:9], v[198:201], v[238:241], v[6:9]
	v_mfma_f32_16x16x32_bf16 v[0:3], v[206:209], v[238:241], v[0:3]
	s_add_i32 s24, s24, 2
	s_add_u32 s22, s22, 0x100
	s_addc_u32 s23, s23, 0
	s_add_u32 s9, s9, 0x100
	s_addc_u32 s10, s10, 0
	s_cmp_gt_u32 s24, 13
	s_barrier
	s_cbranch_scc0 .LBB0_228
	s_and_b64 vcc, exec, s[44:45]
	s_cbranch_vccz .LBB0_231
	s_barrier

.Lpeelmid_252:
	s_add_i32 s3, 0, 0x18000
	v_add_u32_e32 v164, s3, v141
	s_add_i32 s6, 0, 0x1c000
	ds_read_b128 v[144:147], v164
	ds_read_b128 v[148:151], v164 offset:1024
	ds_read_b128 v[172:175], v164 offset:2048
	ds_read_b128 v[190:193], v164 offset:3072
	v_add_u32_e32 v164, s6, v141
	ds_read_b128 v[194:197], v164
	ds_read_b128 v[198:201], v164 offset:1024
	ds_read_b128 v[202:205], v164 offset:2048
	ds_read_b128 v[206:209], v164 offset:3072
	s_add_u32 s4, s14, 0x80000
	s_addc_u32 s5, s15, 0
	s_mov_b32 m0, s31
	ds_read_b128 v[210:213], v143 offset:32768
	ds_read_b128 v[214:217], v143 offset:33792
	ds_read_b128 v[218:221], v143 offset:34816
	ds_read_b128 v[222:225], v143 offset:35840
	ds_read_b128 v[226:229], v143 offset:36864
	ds_read_b128 v[230:233], v143 offset:37888
	ds_read_b128 v[234:237], v143 offset:38912
	ds_read_b128 v[238:241], v143 offset:39936
	global_load_lds_dwordx4 v134, s[4:5]
	v_lshl_add_u64 v[244:245], s[4:5], 0, v[132:133]
	s_mov_b32 m0, s34
	s_nop 0
	global_load_lds_dwordx4 v132, s[4:5]
	s_waitcnt vmcnt(8) lgkmcnt(0)
	s_barrier
	v_mfma_f32_16x16x32_bf16 v[126:129], v[144:147], v[210:213], v[126:129]
	v_mfma_f32_16x16x32_bf16 v[122:125], v[172:175], v[210:213], v[122:125]
	v_mfma_f32_16x16x32_bf16 v[118:121], v[144:147], v[218:221], v[118:121]
	v_mfma_f32_16x16x32_bf16 v[114:117], v[172:175], v[218:221], v[114:117]
	v_mfma_f32_16x16x32_bf16 v[110:113], v[144:147], v[226:229], v[110:113]
	v_mfma_f32_16x16x32_bf16 v[106:109], v[172:175], v[226:229], v[106:109]
	v_mfma_f32_16x16x32_bf16 v[102:105], v[144:147], v[234:237], v[102:105]
	v_mfma_f32_16x16x32_bf16 v[98:101], v[172:175], v[234:237], v[98:101]
	v_mfma_f32_16x16x32_bf16 v[126:129], v[148:151], v[214:217], v[126:129]
	v_mfma_f32_16x16x32_bf16 v[122:125], v[190:193], v[214:217], v[122:125]
	v_mfma_f32_16x16x32_bf16 v[118:121], v[148:151], v[222:225], v[118:121]
	v_mfma_f32_16x16x32_bf16 v[114:117], v[190:193], v[222:225], v[114:117]
	v_mfma_f32_16x16x32_bf16 v[110:113], v[148:151], v[230:233], v[110:113]
	v_mfma_f32_16x16x32_bf16 v[106:109], v[190:193], v[230:233], v[106:109]
	v_mfma_f32_16x16x32_bf16 v[102:105], v[148:151], v[238:241], v[102:105]
	v_mfma_f32_16x16x32_bf16 v[98:101], v[190:193], v[238:241], v[98:101]
	v_mfma_f32_16x16x32_bf16 v[66:69], v[194:197], v[210:213], v[66:69]
	v_mfma_f32_16x16x32_bf16 v[58:61], v[202:205], v[210:213], v[58:61]
	v_mfma_f32_16x16x32_bf16 v[54:57], v[194:197], v[218:221], v[54:57]
	v_mfma_f32_16x16x32_bf16 v[50:53], v[202:205], v[218:221], v[50:53]
	v_mfma_f32_16x16x32_bf16 v[46:49], v[194:197], v[226:229], v[46:49]
	v_mfma_f32_16x16x32_bf16 v[42:45], v[202:205], v[226:229], v[42:45]
	v_mfma_f32_16x16x32_bf16 v[38:41], v[194:197], v[234:237], v[38:41]
	v_mfma_f32_16x16x32_bf16 v[34:37], v[202:205], v[234:237], v[34:37]
	v_mfma_f32_16x16x32_bf16 v[66:69], v[198:201], v[214:217], v[66:69]
	v_mfma_f32_16x16x32_bf16 v[58:61], v[206:209], v[214:217], v[58:61]
	v_mfma_f32_16x16x32_bf16 v[54:57], v[198:201], v[222:225], v[54:57]
	v_mfma_f32_16x16x32_bf16 v[50:53], v[206:209], v[222:225], v[50:53]
	v_mfma_f32_16x16x32_bf16 v[46:49], v[198:201], v[230:233], v[46:49]
	v_mfma_f32_16x16x32_bf16 v[42:45], v[206:209], v[230:233], v[42:45]
	v_mfma_f32_16x16x32_bf16 v[38:41], v[198:201], v[238:241], v[38:41]
	v_mfma_f32_16x16x32_bf16 v[34:37], v[206:209], v[238:241], v[34:37]
	s_barrier
	s_add_i32 s3, s3, s26
	v_lshl_add_u64 v[162:163], v[162:163], 0, s[70:71]
	s_mov_b32 m0, s3
	ds_read_b128 v[210:213], v143 offset:49152
	ds_read_b128 v[214:217], v143 offset:50176
	ds_read_b128 v[218:221], v143 offset:51200
	ds_read_b128 v[222:225], v143 offset:52224
	ds_read_b128 v[226:229], v143 offset:53248
	ds_read_b128 v[230:233], v143 offset:54272
	ds_read_b128 v[234:237], v143 offset:55296
	ds_read_b128 v[238:241], v143 offset:56320
	global_load_lds_dwordx4 v[162:163], off
	s_add_i32 m0, s3, 0x2000
	s_add_u32 s0, s0, 0x80080
	v_lshl_add_u64 v[162:163], v[166:167], 0, s[70:71]
	s_addc_u32 s1, s1, 0
	s_add_i32 s3, s6, s26
	global_load_lds_dwordx4 v[162:163], off
	s_mov_b32 m0, s3
	s_nop 0
	global_load_lds_dwordx4 v4, s[0:1]
	s_add_i32 m0, s3, 0x2000
	s_nop 0
	global_load_lds_dwordx4 v130, s[0:1]
	v_lshl_add_u64 v[162:163], v[176:177], 0, s[70:71]
	s_mov_b32 m0, s35
	s_nop 0
	global_load_lds_dwordx4 v[162:163], off
	v_lshl_add_u64 v[162:163], v[242:243], 0, s[70:71]
	s_mov_b32 m0, s36
	s_nop 0
	global_load_lds_dwordx4 v[162:163], off
	s_waitcnt vmcnt(8) lgkmcnt(0)
	s_barrier
	v_mfma_f32_16x16x32_bf16 v[94:97], v[144:147], v[210:213], v[94:97]
	v_mfma_f32_16x16x32_bf16 v[90:93], v[172:175], v[210:213], v[90:93]
	v_mfma_f32_16x16x32_bf16 v[86:89], v[144:147], v[218:221], v[86:89]
	v_mfma_f32_16x16x32_bf16 v[82:85], v[172:175], v[218:221], v[82:85]
	v_mfma_f32_16x16x32_bf16 v[78:81], v[144:147], v[226:229], v[78:81]
	v_mfma_f32_16x16x32_bf16 v[74:77], v[172:175], v[226:229], v[74:77]
	v_mfma_f32_16x16x32_bf16 v[70:73], v[144:147], v[234:237], v[70:73]
	v_mfma_f32_16x16x32_bf16 v[62:65], v[172:175], v[234:237], v[62:65]
	v_mfma_f32_16x16x32_bf16 v[94:97], v[148:151], v[214:217], v[94:97]
	v_mfma_f32_16x16x32_bf16 v[90:93], v[190:193], v[214:217], v[90:93]
	v_mfma_f32_16x16x32_bf16 v[86:89], v[148:151], v[222:225], v[86:89]
	v_mfma_f32_16x16x32_bf16 v[82:85], v[190:193], v[222:225], v[82:85]
	v_mfma_f32_16x16x32_bf16 v[78:81], v[148:151], v[230:233], v[78:81]
	v_mfma_f32_16x16x32_bf16 v[74:77], v[190:193], v[230:233], v[74:77]
	v_mfma_f32_16x16x32_bf16 v[70:73], v[148:151], v[238:241], v[70:73]
	v_mfma_f32_16x16x32_bf16 v[62:65], v[190:193], v[238:241], v[62:65]
	v_mfma_f32_16x16x32_bf16 v[30:33], v[194:197], v[210:213], v[30:33]
	v_mfma_f32_16x16x32_bf16 v[26:29], v[202:205], v[210:213], v[26:29]
	v_mfma_f32_16x16x32_bf16 v[22:25], v[194:197], v[218:221], v[22:25]
	v_mfma_f32_16x16x32_bf16 v[18:21], v[202:205], v[218:221], v[18:21]
	v_mfma_f32_16x16x32_bf16 v[14:17], v[194:197], v[226:229], v[14:17]
	v_mfma_f32_16x16x32_bf16 v[10:13], v[202:205], v[226:229], v[10:13]
	v_mfma_f32_16x16x32_bf16 v[6:9], v[194:197], v[234:237], v[6:9]
	v_mfma_f32_16x16x32_bf16 v[0:3], v[202:205], v[234:237], v[0:3]
	v_mfma_f32_16x16x32_bf16 v[30:33], v[198:201], v[214:217], v[30:33]
	v_mfma_f32_16x16x32_bf16 v[26:29], v[206:209], v[214:217], v[26:29]
	v_mfma_f32_16x16x32_bf16 v[22:25], v[198:201], v[222:225], v[22:25]
	v_mfma_f32_16x16x32_bf16 v[18:21], v[206:209], v[222:225], v[18:21]
	v_mfma_f32_16x16x32_bf16 v[14:17], v[198:201], v[230:233], v[14:17]
	v_mfma_f32_16x16x32_bf16 v[10:13], v[206:209], v[230:233], v[10:13]
	v_mfma_f32_16x16x32_bf16 v[6:9], v[198:201], v[238:241], v[6:9]
	v_mfma_f32_16x16x32_bf16 v[0:3], v[206:209], v[238:241], v[0:3]
	s_add_i32 s24, s24, 2
	s_add_u32 s22, s22, 0x100
	s_addc_u32 s23, s23, 0
	s_add_u32 s9, s9, 0x100
	s_addc_u32 s10, s10, 0
	s_cmp_gt_u32 s24, 29
	s_barrier
	s_cbranch_scc0 .LBB0_252
	s_and_b64 vcc, exec, s[44:45]
	s_cbranch_vccz .LBB0_255
	s_barrier

.Lpeelmid_852:
	s_add_i32 s3, 0, 0x18000
	v_add_u32_e32 v167, s3, v163
	s_add_i32 s6, 0, 0x1c000
	ds_read_b128 v[140:143], v167
	ds_read_b128 v[144:147], v167 offset:1024
	ds_read_b128 v[148:151], v167 offset:2048
	ds_read_b128 v[172:175], v167 offset:3072
	v_add_u32_e32 v167, s6, v163
	ds_read_b128 v[190:193], v167
	ds_read_b128 v[194:197], v167 offset:1024
	ds_read_b128 v[198:201], v167 offset:2048
	ds_read_b128 v[202:205], v167 offset:3072
	s_add_u32 s4, s14, 0x80000
	s_addc_u32 s5, s15, 0
	s_mov_b32 m0, s30
	ds_read_b128 v[206:209], v166 offset:32768
	ds_read_b128 v[210:213], v166 offset:33792
	ds_read_b128 v[214:217], v166 offset:34816
	ds_read_b128 v[218:221], v166 offset:35840
	ds_read_b128 v[222:225], v166 offset:36864
	ds_read_b128 v[226:229], v166 offset:37888
	ds_read_b128 v[230:233], v166 offset:38912
	ds_read_b128 v[234:237], v166 offset:39936
	global_load_lds_dwordx4 v130, s[4:5]
	v_lshl_add_u64 v[244:245], s[4:5], 0, v[132:133]
	s_mov_b32 m0, s31
	s_nop 0
	global_load_lds_dwordx4 v132, s[4:5]
	s_waitcnt vmcnt(8) lgkmcnt(0)
	s_barrier
	v_mfma_f32_16x16x32_bf16 v[126:129], v[140:143], v[206:209], v[126:129]
	v_mfma_f32_16x16x32_bf16 v[122:125], v[148:151], v[206:209], v[122:125]
	v_mfma_f32_16x16x32_bf16 v[118:121], v[140:143], v[214:217], v[118:121]
	v_mfma_f32_16x16x32_bf16 v[114:117], v[148:151], v[214:217], v[114:117]
	v_mfma_f32_16x16x32_bf16 v[110:113], v[140:143], v[222:225], v[110:113]
	v_mfma_f32_16x16x32_bf16 v[106:109], v[148:151], v[222:225], v[106:109]
	v_mfma_f32_16x16x32_bf16 v[102:105], v[140:143], v[230:233], v[102:105]
	v_mfma_f32_16x16x32_bf16 v[98:101], v[148:151], v[230:233], v[98:101]
	v_mfma_f32_16x16x32_bf16 v[126:129], v[144:147], v[210:213], v[126:129]
	v_mfma_f32_16x16x32_bf16 v[122:125], v[172:175], v[210:213], v[122:125]
	v_mfma_f32_16x16x32_bf16 v[118:121], v[144:147], v[218:221], v[118:121]
	v_mfma_f32_16x16x32_bf16 v[114:117], v[172:175], v[218:221], v[114:117]
	v_mfma_f32_16x16x32_bf16 v[110:113], v[144:147], v[226:229], v[110:113]
	v_mfma_f32_16x16x32_bf16 v[106:109], v[172:175], v[226:229], v[106:109]
	v_mfma_f32_16x16x32_bf16 v[102:105], v[144:147], v[234:237], v[102:105]
	v_mfma_f32_16x16x32_bf16 v[98:101], v[172:175], v[234:237], v[98:101]
	v_mfma_f32_16x16x32_bf16 v[62:65], v[190:193], v[206:209], v[62:65]
	v_mfma_f32_16x16x32_bf16 v[58:61], v[198:201], v[206:209], v[58:61]
	v_mfma_f32_16x16x32_bf16 v[54:57], v[190:193], v[214:217], v[54:57]
	v_mfma_f32_16x16x32_bf16 v[50:53], v[198:201], v[214:217], v[50:53]
	v_mfma_f32_16x16x32_bf16 v[46:49], v[190:193], v[222:225], v[46:49]
	v_mfma_f32_16x16x32_bf16 v[42:45], v[198:201], v[222:225], v[42:45]
	v_mfma_f32_16x16x32_bf16 v[38:41], v[190:193], v[230:233], v[38:41]
	v_mfma_f32_16x16x32_bf16 v[34:37], v[198:201], v[230:233], v[34:37]
	v_mfma_f32_16x16x32_bf16 v[62:65], v[194:197], v[210:213], v[62:65]
	v_mfma_f32_16x16x32_bf16 v[58:61], v[202:205], v[210:213], v[58:61]
	v_mfma_f32_16x16x32_bf16 v[54:57], v[194:197], v[218:221], v[54:57]
	v_mfma_f32_16x16x32_bf16 v[50:53], v[202:205], v[218:221], v[50:53]
	v_mfma_f32_16x16x32_bf16 v[46:49], v[194:197], v[226:229], v[46:49]
	v_mfma_f32_16x16x32_bf16 v[42:45], v[202:205], v[226:229], v[42:45]
	v_mfma_f32_16x16x32_bf16 v[38:41], v[194:197], v[234:237], v[38:41]
	v_mfma_f32_16x16x32_bf16 v[34:37], v[202:205], v[234:237], v[34:37]
	s_barrier
	s_add_i32 s3, s3, s11
	v_lshl_add_u64 v[176:177], v[176:177], 0, s[70:71]
	s_mov_b32 m0, s3
	ds_read_b128 v[206:209], v166 offset:49152
	ds_read_b128 v[210:213], v166 offset:50176
	ds_read_b128 v[214:217], v166 offset:51200
	ds_read_b128 v[218:221], v166 offset:52224
	ds_read_b128 v[222:225], v166 offset:53248
	ds_read_b128 v[226:229], v166 offset:54272
	ds_read_b128 v[230:233], v166 offset:55296
	ds_read_b128 v[234:237], v166 offset:56320
	global_load_lds_dwordx4 v[176:177], off
	s_add_i32 m0, s3, 0x2000
	s_add_u32 s0, s0, 0x80080
	v_lshl_add_u64 v[176:177], v[238:239], 0, s[70:71]
	s_addc_u32 s1, s1, 0
	s_add_i32 s3, s6, s11
	global_load_lds_dwordx4 v[176:177], off
	s_mov_b32 m0, s3
	s_nop 0
	global_load_lds_dwordx4 v4, s[0:1]
	s_add_i32 m0, s3, 0x2000
	s_nop 0
	global_load_lds_dwordx4 v134, s[0:1]
	v_lshl_add_u64 v[176:177], v[240:241], 0, s[70:71]
	s_mov_b32 m0, s34
	s_nop 0
	global_load_lds_dwordx4 v[176:177], off
	v_lshl_add_u64 v[176:177], v[242:243], 0, s[70:71]
	s_mov_b32 m0, s35
	s_nop 0
	global_load_lds_dwordx4 v[176:177], off
	s_waitcnt vmcnt(8) lgkmcnt(0)
	s_barrier
	v_mfma_f32_16x16x32_bf16 v[94:97], v[140:143], v[206:209], v[94:97]
	v_mfma_f32_16x16x32_bf16 v[90:93], v[148:151], v[206:209], v[90:93]
	v_mfma_f32_16x16x32_bf16 v[86:89], v[140:143], v[214:217], v[86:89]
	v_mfma_f32_16x16x32_bf16 v[82:85], v[148:151], v[214:217], v[82:85]
	v_mfma_f32_16x16x32_bf16 v[78:81], v[140:143], v[222:225], v[78:81]
	v_mfma_f32_16x16x32_bf16 v[74:77], v[148:151], v[222:225], v[74:77]
	v_mfma_f32_16x16x32_bf16 v[70:73], v[140:143], v[230:233], v[70:73]
	v_mfma_f32_16x16x32_bf16 v[66:69], v[148:151], v[230:233], v[66:69]
	v_mfma_f32_16x16x32_bf16 v[94:97], v[144:147], v[210:213], v[94:97]
	v_mfma_f32_16x16x32_bf16 v[90:93], v[172:175], v[210:213], v[90:93]
	v_mfma_f32_16x16x32_bf16 v[86:89], v[144:147], v[218:221], v[86:89]
	v_mfma_f32_16x16x32_bf16 v[82:85], v[172:175], v[218:221], v[82:85]
	v_mfma_f32_16x16x32_bf16 v[78:81], v[144:147], v[226:229], v[78:81]
	v_mfma_f32_16x16x32_bf16 v[74:77], v[172:175], v[226:229], v[74:77]
	v_mfma_f32_16x16x32_bf16 v[70:73], v[144:147], v[234:237], v[70:73]
	v_mfma_f32_16x16x32_bf16 v[66:69], v[172:175], v[234:237], v[66:69]
	v_mfma_f32_16x16x32_bf16 v[30:33], v[190:193], v[206:209], v[30:33]
	v_mfma_f32_16x16x32_bf16 v[26:29], v[198:201], v[206:209], v[26:29]
	v_mfma_f32_16x16x32_bf16 v[22:25], v[190:193], v[214:217], v[22:25]
	v_mfma_f32_16x16x32_bf16 v[18:21], v[198:201], v[214:217], v[18:21]
	v_mfma_f32_16x16x32_bf16 v[14:17], v[190:193], v[222:225], v[14:17]
	v_mfma_f32_16x16x32_bf16 v[10:13], v[198:201], v[222:225], v[10:13]
	v_mfma_f32_16x16x32_bf16 v[6:9], v[190:193], v[230:233], v[6:9]
	v_mfma_f32_16x16x32_bf16 v[0:3], v[198:201], v[230:233], v[0:3]
	v_mfma_f32_16x16x32_bf16 v[30:33], v[194:197], v[210:213], v[30:33]
	v_mfma_f32_16x16x32_bf16 v[26:29], v[202:205], v[210:213], v[26:29]
	v_mfma_f32_16x16x32_bf16 v[22:25], v[194:197], v[218:221], v[22:25]
	v_mfma_f32_16x16x32_bf16 v[18:21], v[202:205], v[218:221], v[18:21]
	v_mfma_f32_16x16x32_bf16 v[14:17], v[194:197], v[226:229], v[14:17]
	v_mfma_f32_16x16x32_bf16 v[10:13], v[202:205], v[226:229], v[10:13]
	v_mfma_f32_16x16x32_bf16 v[6:9], v[194:197], v[234:237], v[6:9]
	v_mfma_f32_16x16x32_bf16 v[0:3], v[202:205], v[234:237], v[0:3]
	s_add_i32 s28, s28, 2
	s_add_u32 s22, s22, 0x100
	s_addc_u32 s23, s23, 0
	s_add_u32 s9, s9, 0x100
	s_addc_u32 s25, s25, 0
	s_cmp_gt_u32 s28, 29
	s_barrier
	s_cbranch_scc0 .LBB0_852
	s_and_b64 vcc, exec, s[48:49]
	s_cbranch_vccz .LBB0_855
	s_barrier
